# hot loop heads (two attention tile loops, eight GEMM K-loops) aligned to 64 bytes with .p2align 6
# speedup vs baseline: 1.0041x; 1.0041x over previous
.LBB0_158:
	s_ashr_i32 s31, s30, 31
	s_lshl_b64 s[34:35], s[30:31], 20
	s_add_u32 s34, s50, s34
	s_addc_u32 s35, s51, s35
	s_and_b64 s[36:37], s[2:3], exec
	s_cselect_b32 s0, s35, s41
	s_cselect_b32 s5, s34, s40
	s_ashr_i32 s29, s28, 31
	s_lshl_b64 s[36:37], s[28:29], 20
	s_add_u32 s36, s17, s36
	s_addc_u32 s37, s27, s37
	s_and_b64 s[44:45], s[2:3], exec
	s_cselect_b32 s29, s37, s43
	s_cselect_b32 s31, s36, s42
	s_add_u32 s40, s40, 0x80080
	s_addc_u32 s41, s41, 0
	s_add_u32 s33, s42, 0x100
	v_mov_b32_e32 v0, 0
	s_addc_u32 s48, s43, 0
	s_mov_b32 s49, -2
	v_mov_b32_e32 v1, v0
	v_mov_b32_e32 v2, v0
	v_mov_b32_e32 v3, v0
	v_mov_b32_e32 v4, v0
	v_mov_b32_e32 v5, v0
	v_mov_b32_e32 v6, v0
	v_mov_b32_e32 v7, v0
	v_mov_b32_e32 v16, v0
	v_mov_b32_e32 v17, v0
	v_mov_b32_e32 v18, v0
	v_mov_b32_e32 v19, v0
	v_mov_b32_e32 v20, v0
	v_mov_b32_e32 v21, v0
	v_mov_b32_e32 v22, v0
	v_mov_b32_e32 v23, v0
	v_mov_b32_e32 v32, v0
	v_mov_b32_e32 v33, v0
	v_mov_b32_e32 v34, v0
	v_mov_b32_e32 v35, v0
	v_mov_b32_e32 v36, v0
	v_mov_b32_e32 v37, v0
	v_mov_b32_e32 v38, v0
	v_mov_b32_e32 v39, v0
	v_mov_b32_e32 v48, v0
	v_mov_b32_e32 v49, v0
	v_mov_b32_e32 v50, v0
	v_mov_b32_e32 v51, v0
	v_mov_b32_e32 v52, v0
	v_mov_b32_e32 v53, v0
	v_mov_b32_e32 v54, v0
	v_mov_b32_e32 v55, v0
	v_mov_b32_e32 v8, v0
	v_mov_b32_e32 v9, v0
	v_mov_b32_e32 v10, v0
	v_mov_b32_e32 v11, v0
	v_mov_b32_e32 v12, v0
	v_mov_b32_e32 v13, v0
	v_mov_b32_e32 v14, v0
	v_mov_b32_e32 v15, v0
	v_mov_b32_e32 v24, v0
	v_mov_b32_e32 v25, v0
	v_mov_b32_e32 v26, v0
	v_mov_b32_e32 v27, v0
	v_mov_b32_e32 v28, v0
	v_mov_b32_e32 v29, v0
	v_mov_b32_e32 v30, v0
	v_mov_b32_e32 v31, v0
	v_mov_b32_e32 v40, v0
	v_mov_b32_e32 v41, v0
	v_mov_b32_e32 v42, v0
	v_mov_b32_e32 v43, v0
	v_mov_b32_e32 v44, v0
	v_mov_b32_e32 v45, v0
	v_mov_b32_e32 v46, v0
	v_mov_b32_e32 v47, v0
	v_mov_b32_e32 v56, v0
	v_mov_b32_e32 v57, v0
	v_mov_b32_e32 v58, v0
	v_mov_b32_e32 v59, v0
	v_mov_b32_e32 v60, v0
	v_mov_b32_e32 v61, v0
	v_mov_b32_e32 v62, v0
	v_mov_b32_e32 v63, v0
	v_mov_b32_e32 v64, v0
	v_mov_b32_e32 v65, v0
	v_mov_b32_e32 v66, v0
	v_mov_b32_e32 v67, v0
	v_mov_b32_e32 v68, v0
	v_mov_b32_e32 v69, v0
	v_mov_b32_e32 v70, v0
	v_mov_b32_e32 v71, v0
	v_mov_b32_e32 v80, v0
	v_mov_b32_e32 v81, v0
	v_mov_b32_e32 v82, v0
	v_mov_b32_e32 v83, v0
	v_mov_b32_e32 v84, v0
	v_mov_b32_e32 v85, v0
	v_mov_b32_e32 v86, v0
	v_mov_b32_e32 v87, v0
	v_mov_b32_e32 v96, v0
	v_mov_b32_e32 v97, v0
	v_mov_b32_e32 v98, v0
	v_mov_b32_e32 v99, v0
	v_mov_b32_e32 v100, v0
	v_mov_b32_e32 v101, v0
	v_mov_b32_e32 v102, v0
	v_mov_b32_e32 v103, v0
	v_mov_b32_e32 v112, v0
	v_mov_b32_e32 v113, v0
	v_mov_b32_e32 v114, v0
	v_mov_b32_e32 v115, v0
	v_mov_b32_e32 v116, v0
	v_mov_b32_e32 v117, v0
	v_mov_b32_e32 v118, v0
	v_mov_b32_e32 v119, v0
	v_mov_b32_e32 v72, v0
	v_mov_b32_e32 v73, v0
	v_mov_b32_e32 v74, v0
	v_mov_b32_e32 v75, v0
	v_mov_b32_e32 v76, v0
	v_mov_b32_e32 v77, v0
	v_mov_b32_e32 v78, v0
	v_mov_b32_e32 v79, v0
	v_mov_b32_e32 v88, v0
	v_mov_b32_e32 v89, v0
	v_mov_b32_e32 v90, v0
	v_mov_b32_e32 v91, v0
	v_mov_b32_e32 v92, v0
	v_mov_b32_e32 v93, v0
	v_mov_b32_e32 v94, v0
	v_mov_b32_e32 v95, v0
	v_mov_b32_e32 v104, v0
	v_mov_b32_e32 v105, v0
	v_mov_b32_e32 v106, v0
	v_mov_b32_e32 v107, v0
	v_mov_b32_e32 v108, v0
	v_mov_b32_e32 v109, v0
	v_mov_b32_e32 v110, v0
	v_mov_b32_e32 v111, v0
	v_mov_b32_e32 v120, v0
	v_mov_b32_e32 v121, v0
	v_mov_b32_e32 v122, v0
	v_mov_b32_e32 v123, v0
	v_mov_b32_e32 v124, v0
	v_mov_b32_e32 v125, v0
	v_mov_b32_e32 v126, v0
	v_mov_b32_e32 v127, v0
	.p2align 6

.LBB0_280:
	v_sub_f32_e32 v0, v18, v186
	v_exp_f32_e32 v0, v0
	v_sub_f32_e32 v18, v19, v186
	v_exp_f32_e32 v18, v18
	v_sub_f32_e32 v19, v20, v186
	v_exp_f32_e32 v19, v19
	v_sub_f32_e32 v20, v21, v186
	v_exp_f32_e32 v20, v20
	v_sub_f32_e32 v22, v22, v186
	v_add_f32_e32 v21, 0, v0
	v_exp_f32_e32 v22, v22
	v_sub_f32_e32 v23, v23, v186
	v_add_f32_e32 v21, v18, v21
	v_exp_f32_e32 v23, v23
	v_sub_f32_e32 v24, v24, v186
	v_add_f32_e32 v21, v19, v21
	v_exp_f32_e32 v24, v24
	v_sub_f32_e32 v25, v25, v186
	v_add_f32_e32 v21, v20, v21
	v_exp_f32_e32 v25, v25
	v_sub_f32_e32 v26, v26, v186
	v_add_f32_e32 v21, v22, v21
	v_exp_f32_e32 v26, v26
	v_sub_f32_e32 v27, v27, v186
	v_add_f32_e32 v21, v23, v21
	v_exp_f32_e32 v27, v27
	v_sub_f32_e32 v28, v28, v186
	v_add_f32_e32 v21, v24, v21
	v_exp_f32_e32 v28, v28
	v_sub_f32_e32 v29, v29, v186
	v_add_f32_e32 v21, v25, v21
	v_exp_f32_e32 v29, v29
	v_sub_f32_e32 v30, v30, v186
	v_add_f32_e32 v21, v26, v21
	v_exp_f32_e32 v30, v30
	v_sub_f32_e32 v31, v31, v186
	v_add_f32_e32 v21, v27, v21
	v_exp_f32_e32 v31, v31
	v_sub_f32_e32 v32, v32, v186
	v_add_f32_e32 v21, v28, v21
	v_exp_f32_e32 v32, v32
	v_sub_f32_e32 v33, v33, v186
	v_add_f32_e32 v21, v29, v21
	v_exp_f32_e32 v33, v33
	v_add_f32_e32 v21, v30, v21
	v_add_f32_e32 v21, v31, v21
	v_cvt_pk_bf16_f32 v182, v0, v18
	v_add_u32_e32 v0, s3, v242
	v_add_f32_e32 v21, v32, v21
	v_cvt_pk_bf16_f32 v183, v19, v20
	v_lshlrev_b64 v[18:19], 9, v[0:1]
	v_add_u32_e32 v0, s3, v243
	v_add_f32_e32 v203, v33, v21
	v_lshl_add_u64 v[204:205], v[40:41], 0, v[18:19]
	v_lshlrev_b64 v[18:19], 9, v[0:1]
	s_lshl_b32 s43, s2, 2
	v_cvt_pk_bf16_f32 v178, v26, v27
	v_cvt_pk_bf16_f32 v179, v28, v29
	v_cvt_pk_bf16_f32 v180, v30, v31
	v_cvt_pk_bf16_f32 v181, v32, v33
	v_cvt_pk_bf16_f32 v184, v22, v23
	v_cvt_pk_bf16_f32 v185, v24, v25
	v_fmac_f32_e32 v203, 0, v42
	v_lshl_add_u64 v[206:207], v[38:39], 0, v[18:19]
	v_lshl_add_u64 v[208:209], v[36:37], 0, s[18:19]
	v_lshl_add_u64 v[210:211], v[34:35], 0, s[18:19]
	v_mov_b64_e32 v[32:33], v[16:17]
	v_mov_b64_e32 v[48:49], v[16:17]
	v_mov_b64_e32 v[64:65], v[16:17]
	v_mov_b64_e32 v[80:81], v[16:17]
	v_mov_b64_e32 v[96:97], v[16:17]
	v_mov_b64_e32 v[112:113], v[16:17]
	v_mov_b64_e32 v[128:129], v[16:17]
	s_add_i32 s44, s43, 4
	s_add_i32 s45, s33, 0x60
	s_mov_b32 s0, 1
	s_mov_b32 s46, 0
	s_mov_b32 s47, 3
	v_mov_b64_e32 v[30:31], v[14:15]
	v_mov_b64_e32 v[28:29], v[12:13]
	v_mov_b64_e32 v[26:27], v[10:11]
	v_mov_b64_e32 v[24:25], v[8:9]
	v_mov_b64_e32 v[22:23], v[6:7]
	v_mov_b64_e32 v[20:21], v[4:5]
	v_mov_b64_e32 v[18:19], v[2:3]
	v_mov_b64_e32 v[46:47], v[14:15]
	v_mov_b64_e32 v[44:45], v[12:13]
	v_mov_b64_e32 v[42:43], v[10:11]
	v_mov_b64_e32 v[40:41], v[8:9]
	v_mov_b64_e32 v[38:39], v[6:7]
	v_mov_b64_e32 v[36:37], v[4:5]
	v_mov_b64_e32 v[34:35], v[2:3]
	v_mov_b64_e32 v[62:63], v[14:15]
	v_mov_b64_e32 v[60:61], v[12:13]
	v_mov_b64_e32 v[58:59], v[10:11]
	v_mov_b64_e32 v[56:57], v[8:9]
	v_mov_b64_e32 v[54:55], v[6:7]
	v_mov_b64_e32 v[52:53], v[4:5]
	v_mov_b64_e32 v[50:51], v[2:3]
	v_mov_b64_e32 v[78:79], v[14:15]
	v_mov_b64_e32 v[76:77], v[12:13]
	v_mov_b64_e32 v[74:75], v[10:11]
	v_mov_b64_e32 v[72:73], v[8:9]
	v_mov_b64_e32 v[70:71], v[6:7]
	v_mov_b64_e32 v[68:69], v[4:5]
	v_mov_b64_e32 v[66:67], v[2:3]
	v_mov_b64_e32 v[94:95], v[14:15]
	v_mov_b64_e32 v[92:93], v[12:13]
	v_mov_b64_e32 v[90:91], v[10:11]
	v_mov_b64_e32 v[88:89], v[8:9]
	v_mov_b64_e32 v[86:87], v[6:7]
	v_mov_b64_e32 v[84:85], v[4:5]
	v_mov_b64_e32 v[82:83], v[2:3]
	v_mov_b64_e32 v[110:111], v[14:15]
	v_mov_b64_e32 v[108:109], v[12:13]
	v_mov_b64_e32 v[106:107], v[10:11]
	v_mov_b64_e32 v[104:105], v[8:9]
	v_mov_b64_e32 v[102:103], v[6:7]
	v_mov_b64_e32 v[100:101], v[4:5]
	v_mov_b64_e32 v[98:99], v[2:3]
	v_mov_b64_e32 v[126:127], v[14:15]
	v_mov_b64_e32 v[124:125], v[12:13]
	v_mov_b64_e32 v[122:123], v[10:11]
	v_mov_b64_e32 v[120:121], v[8:9]
	v_mov_b64_e32 v[118:119], v[6:7]
	v_mov_b64_e32 v[116:117], v[4:5]
	v_mov_b64_e32 v[114:115], v[2:3]
	s_mov_b32 s49, 0
	.p2align 6

.LBB0_373:
	s_ashr_i32 s11, s10, 31
	s_lshl_b64 s[12:13], s[10:11], 20
	s_add_u32 s12, s50, s12
	s_addc_u32 s13, s51, s13
	s_and_b64 s[14:15], s[2:3], exec
	s_cselect_b32 s11, s13, s21
	s_cselect_b32 s41, s12, s20
	s_ashr_i32 s9, s8, 31
	s_lshl_b64 s[14:15], s[8:9], 20
	s_add_u32 s14, s26, s14
	s_addc_u32 s15, s27, s15
	s_and_b64 s[24:25], s[2:3], exec
	s_cselect_b32 s9, s15, s23
	s_cselect_b32 s42, s14, s22
	s_add_u32 s20, s20, 0x80080
	s_addc_u32 s21, s21, 0
	s_add_u32 s43, s22, 0x100
	v_mov_b32_e32 v0, 0
	s_addc_u32 s44, s23, 0
	s_mov_b32 s45, -2
	v_mov_b32_e32 v1, v0
	v_mov_b32_e32 v2, v0
	v_mov_b32_e32 v3, v0
	v_mov_b32_e32 v4, v0
	v_mov_b32_e32 v5, v0
	v_mov_b32_e32 v6, v0
	v_mov_b32_e32 v7, v0
	v_mov_b32_e32 v8, v0
	v_mov_b32_e32 v9, v0
	v_mov_b32_e32 v10, v0
	v_mov_b32_e32 v11, v0
	v_mov_b32_e32 v20, v0
	v_mov_b32_e32 v21, v0
	v_mov_b32_e32 v22, v0
	v_mov_b32_e32 v23, v0
	v_mov_b32_e32 v24, v0
	v_mov_b32_e32 v25, v0
	v_mov_b32_e32 v26, v0
	v_mov_b32_e32 v27, v0
	v_mov_b32_e32 v36, v0
	v_mov_b32_e32 v37, v0
	v_mov_b32_e32 v38, v0
	v_mov_b32_e32 v39, v0
	v_mov_b32_e32 v40, v0
	v_mov_b32_e32 v41, v0
	v_mov_b32_e32 v42, v0
	v_mov_b32_e32 v43, v0
	v_mov_b32_e32 v52, v0
	v_mov_b32_e32 v53, v0
	v_mov_b32_e32 v54, v0
	v_mov_b32_e32 v55, v0
	v_mov_b32_e32 v12, v0
	v_mov_b32_e32 v13, v0
	v_mov_b32_e32 v14, v0
	v_mov_b32_e32 v15, v0
	v_mov_b32_e32 v16, v0
	v_mov_b32_e32 v17, v0
	v_mov_b32_e32 v18, v0
	v_mov_b32_e32 v19, v0
	v_mov_b32_e32 v28, v0
	v_mov_b32_e32 v29, v0
	v_mov_b32_e32 v30, v0
	v_mov_b32_e32 v31, v0
	v_mov_b32_e32 v32, v0
	v_mov_b32_e32 v33, v0
	v_mov_b32_e32 v34, v0
	v_mov_b32_e32 v35, v0
	v_mov_b32_e32 v44, v0
	v_mov_b32_e32 v45, v0
	v_mov_b32_e32 v46, v0
	v_mov_b32_e32 v47, v0
	v_mov_b32_e32 v48, v0
	v_mov_b32_e32 v49, v0
	v_mov_b32_e32 v50, v0
	v_mov_b32_e32 v51, v0
	v_mov_b32_e32 v56, v0
	v_mov_b32_e32 v57, v0
	v_mov_b32_e32 v58, v0
	v_mov_b32_e32 v59, v0
	v_mov_b32_e32 v60, v0
	v_mov_b32_e32 v61, v0
	v_mov_b32_e32 v62, v0
	v_mov_b32_e32 v63, v0
	v_mov_b32_e32 v64, v0
	v_mov_b32_e32 v65, v0
	v_mov_b32_e32 v66, v0
	v_mov_b32_e32 v67, v0
	v_mov_b32_e32 v68, v0
	v_mov_b32_e32 v69, v0
	v_mov_b32_e32 v70, v0
	v_mov_b32_e32 v71, v0
	v_mov_b32_e32 v72, v0
	v_mov_b32_e32 v73, v0
	v_mov_b32_e32 v74, v0
	v_mov_b32_e32 v75, v0
	v_mov_b32_e32 v84, v0
	v_mov_b32_e32 v85, v0
	v_mov_b32_e32 v86, v0
	v_mov_b32_e32 v87, v0
	v_mov_b32_e32 v88, v0
	v_mov_b32_e32 v89, v0
	v_mov_b32_e32 v90, v0
	v_mov_b32_e32 v91, v0
	v_mov_b32_e32 v100, v0
	v_mov_b32_e32 v101, v0
	v_mov_b32_e32 v102, v0
	v_mov_b32_e32 v103, v0
	v_mov_b32_e32 v104, v0
	v_mov_b32_e32 v105, v0
	v_mov_b32_e32 v106, v0
	v_mov_b32_e32 v107, v0
	v_mov_b32_e32 v116, v0
	v_mov_b32_e32 v117, v0
	v_mov_b32_e32 v118, v0
	v_mov_b32_e32 v119, v0
	v_mov_b32_e32 v76, v0
	v_mov_b32_e32 v77, v0
	v_mov_b32_e32 v78, v0
	v_mov_b32_e32 v79, v0
	v_mov_b32_e32 v80, v0
	v_mov_b32_e32 v81, v0
	v_mov_b32_e32 v82, v0
	v_mov_b32_e32 v83, v0
	v_mov_b32_e32 v92, v0
	v_mov_b32_e32 v93, v0
	v_mov_b32_e32 v94, v0
	v_mov_b32_e32 v95, v0
	v_mov_b32_e32 v96, v0
	v_mov_b32_e32 v97, v0
	v_mov_b32_e32 v98, v0
	v_mov_b32_e32 v99, v0
	v_mov_b32_e32 v108, v0
	v_mov_b32_e32 v109, v0
	v_mov_b32_e32 v110, v0
	v_mov_b32_e32 v111, v0
	v_mov_b32_e32 v112, v0
	v_mov_b32_e32 v113, v0
	v_mov_b32_e32 v114, v0
	v_mov_b32_e32 v115, v0
	v_mov_b32_e32 v120, v0
	v_mov_b32_e32 v121, v0
	v_mov_b32_e32 v122, v0
	v_mov_b32_e32 v123, v0
	v_mov_b32_e32 v124, v0
	v_mov_b32_e32 v125, v0
	v_mov_b32_e32 v126, v0
	v_mov_b32_e32 v127, v0
	.p2align 6

.LBB0_504:
	s_ashr_i32 s21, s20, 31
	s_lshl_b64 s[22:23], s[20:21], 20
	s_add_u32 s22, s50, s22
	s_addc_u32 s23, s51, s23
	s_and_b64 s[24:25], s[2:3], exec
	s_cselect_b32 s0, s23, s5
	s_cselect_b32 s21, s22, s4
	s_ashr_i32 s19, s18, 31
	s_lshl_b64 s[24:25], s[18:19], 20
	s_add_u32 s24, s17, s24
	s_addc_u32 s25, s33, s25
	s_and_b64 s[34:35], s[2:3], exec
	s_cselect_b32 s19, s25, s31
	s_cselect_b32 s36, s24, s30
	s_add_u32 s4, s4, 0x80080
	s_addc_u32 s5, s5, 0
	s_add_u32 s37, s30, 0x100
	v_mov_b32_e32 v0, 0
	s_addc_u32 s38, s31, 0
	s_mov_b32 s39, -2
	v_mov_b32_e32 v1, v0
	v_mov_b32_e32 v2, v0
	v_mov_b32_e32 v3, v0
	v_mov_b32_e32 v4, v0
	v_mov_b32_e32 v5, v0
	v_mov_b32_e32 v6, v0
	v_mov_b32_e32 v7, v0
	v_mov_b32_e32 v16, v0
	v_mov_b32_e32 v17, v0
	v_mov_b32_e32 v18, v0
	v_mov_b32_e32 v19, v0
	v_mov_b32_e32 v20, v0
	v_mov_b32_e32 v21, v0
	v_mov_b32_e32 v22, v0
	v_mov_b32_e32 v23, v0
	v_mov_b32_e32 v32, v0
	v_mov_b32_e32 v33, v0
	v_mov_b32_e32 v34, v0
	v_mov_b32_e32 v35, v0
	v_mov_b32_e32 v36, v0
	v_mov_b32_e32 v37, v0
	v_mov_b32_e32 v38, v0
	v_mov_b32_e32 v39, v0
	v_mov_b32_e32 v48, v0
	v_mov_b32_e32 v49, v0
	v_mov_b32_e32 v50, v0
	v_mov_b32_e32 v51, v0
	v_mov_b32_e32 v52, v0
	v_mov_b32_e32 v53, v0
	v_mov_b32_e32 v54, v0
	v_mov_b32_e32 v55, v0
	v_mov_b32_e32 v8, v0
	v_mov_b32_e32 v9, v0
	v_mov_b32_e32 v10, v0
	v_mov_b32_e32 v11, v0
	v_mov_b32_e32 v12, v0
	v_mov_b32_e32 v13, v0
	v_mov_b32_e32 v14, v0
	v_mov_b32_e32 v15, v0
	v_mov_b32_e32 v24, v0
	v_mov_b32_e32 v25, v0
	v_mov_b32_e32 v26, v0
	v_mov_b32_e32 v27, v0
	v_mov_b32_e32 v28, v0
	v_mov_b32_e32 v29, v0
	v_mov_b32_e32 v30, v0
	v_mov_b32_e32 v31, v0
	v_mov_b32_e32 v40, v0
	v_mov_b32_e32 v41, v0
	v_mov_b32_e32 v42, v0
	v_mov_b32_e32 v43, v0
	v_mov_b32_e32 v44, v0
	v_mov_b32_e32 v45, v0
	v_mov_b32_e32 v46, v0
	v_mov_b32_e32 v47, v0
	v_mov_b32_e32 v56, v0
	v_mov_b32_e32 v57, v0
	v_mov_b32_e32 v58, v0
	v_mov_b32_e32 v59, v0
	v_mov_b32_e32 v60, v0
	v_mov_b32_e32 v61, v0
	v_mov_b32_e32 v62, v0
	v_mov_b32_e32 v63, v0
	v_mov_b32_e32 v64, v0
	v_mov_b32_e32 v65, v0
	v_mov_b32_e32 v66, v0
	v_mov_b32_e32 v67, v0
	v_mov_b32_e32 v68, v0
	v_mov_b32_e32 v69, v0
	v_mov_b32_e32 v70, v0
	v_mov_b32_e32 v71, v0
	v_mov_b32_e32 v80, v0
	v_mov_b32_e32 v81, v0
	v_mov_b32_e32 v82, v0
	v_mov_b32_e32 v83, v0
	v_mov_b32_e32 v84, v0
	v_mov_b32_e32 v85, v0
	v_mov_b32_e32 v86, v0
	v_mov_b32_e32 v87, v0
	v_mov_b32_e32 v96, v0
	v_mov_b32_e32 v97, v0
	v_mov_b32_e32 v98, v0
	v_mov_b32_e32 v99, v0
	v_mov_b32_e32 v100, v0
	v_mov_b32_e32 v101, v0
	v_mov_b32_e32 v102, v0
	v_mov_b32_e32 v103, v0
	v_mov_b32_e32 v112, v0
	v_mov_b32_e32 v113, v0
	v_mov_b32_e32 v114, v0
	v_mov_b32_e32 v115, v0
	v_mov_b32_e32 v116, v0
	v_mov_b32_e32 v117, v0
	v_mov_b32_e32 v118, v0
	v_mov_b32_e32 v119, v0
	v_mov_b32_e32 v72, v0
	v_mov_b32_e32 v73, v0
	v_mov_b32_e32 v74, v0
	v_mov_b32_e32 v75, v0
	v_mov_b32_e32 v76, v0
	v_mov_b32_e32 v77, v0
	v_mov_b32_e32 v78, v0
	v_mov_b32_e32 v79, v0
	v_mov_b32_e32 v88, v0
	v_mov_b32_e32 v89, v0
	v_mov_b32_e32 v90, v0
	v_mov_b32_e32 v91, v0
	v_mov_b32_e32 v92, v0
	v_mov_b32_e32 v93, v0
	v_mov_b32_e32 v94, v0
	v_mov_b32_e32 v95, v0
	v_mov_b32_e32 v104, v0
	v_mov_b32_e32 v105, v0
	v_mov_b32_e32 v106, v0
	v_mov_b32_e32 v107, v0
	v_mov_b32_e32 v108, v0
	v_mov_b32_e32 v109, v0
	v_mov_b32_e32 v110, v0
	v_mov_b32_e32 v111, v0
	v_mov_b32_e32 v120, v0
	v_mov_b32_e32 v121, v0
	v_mov_b32_e32 v122, v0
	v_mov_b32_e32 v123, v0
	v_mov_b32_e32 v124, v0
	v_mov_b32_e32 v125, v0
	v_mov_b32_e32 v126, v0
	v_mov_b32_e32 v127, v0
	.p2align 6

.LBB0_735:
	s_ashr_i32 s11, s10, 31
	s_lshl_b64 s[12:13], s[10:11], 20
	s_add_u32 s12, s50, s12
	s_addc_u32 s13, s51, s13
	s_and_b64 s[14:15], s[2:3], exec
	s_cselect_b32 s11, s13, s21
	s_cselect_b32 s41, s12, s20
	s_ashr_i32 s9, s8, 31
	s_lshl_b64 s[14:15], s[8:9], 20
	s_add_u32 s14, s26, s14
	s_addc_u32 s15, s27, s15
	s_and_b64 s[24:25], s[2:3], exec
	s_cselect_b32 s9, s15, s23
	s_cselect_b32 s42, s14, s22
	s_add_u32 s20, s20, 0x80080
	s_addc_u32 s21, s21, 0
	s_add_u32 s43, s22, 0x100
	v_mov_b32_e32 v0, 0
	s_addc_u32 s44, s23, 0
	s_mov_b32 s45, -2
	v_mov_b32_e32 v1, v0
	v_mov_b32_e32 v2, v0
	v_mov_b32_e32 v3, v0
	v_mov_b32_e32 v4, v0
	v_mov_b32_e32 v5, v0
	v_mov_b32_e32 v6, v0
	v_mov_b32_e32 v7, v0
	v_mov_b32_e32 v8, v0
	v_mov_b32_e32 v9, v0
	v_mov_b32_e32 v10, v0
	v_mov_b32_e32 v11, v0
	v_mov_b32_e32 v12, v0
	v_mov_b32_e32 v13, v0
	v_mov_b32_e32 v14, v0
	v_mov_b32_e32 v15, v0
	v_mov_b32_e32 v32, v0
	v_mov_b32_e32 v33, v0
	v_mov_b32_e32 v34, v0
	v_mov_b32_e32 v35, v0
	v_mov_b32_e32 v36, v0
	v_mov_b32_e32 v37, v0
	v_mov_b32_e32 v38, v0
	v_mov_b32_e32 v39, v0
	v_mov_b32_e32 v40, v0
	v_mov_b32_e32 v41, v0
	v_mov_b32_e32 v42, v0
	v_mov_b32_e32 v43, v0
	v_mov_b32_e32 v44, v0
	v_mov_b32_e32 v45, v0
	v_mov_b32_e32 v46, v0
	v_mov_b32_e32 v47, v0
	v_mov_b32_e32 v16, v0
	v_mov_b32_e32 v17, v0
	v_mov_b32_e32 v18, v0
	v_mov_b32_e32 v19, v0
	v_mov_b32_e32 v20, v0
	v_mov_b32_e32 v21, v0
	v_mov_b32_e32 v22, v0
	v_mov_b32_e32 v23, v0
	v_mov_b32_e32 v24, v0
	v_mov_b32_e32 v25, v0
	v_mov_b32_e32 v26, v0
	v_mov_b32_e32 v27, v0
	v_mov_b32_e32 v28, v0
	v_mov_b32_e32 v29, v0
	v_mov_b32_e32 v30, v0
	v_mov_b32_e32 v31, v0
	v_mov_b32_e32 v48, v0
	v_mov_b32_e32 v49, v0
	v_mov_b32_e32 v50, v0
	v_mov_b32_e32 v51, v0
	v_mov_b32_e32 v52, v0
	v_mov_b32_e32 v53, v0
	v_mov_b32_e32 v54, v0
	v_mov_b32_e32 v55, v0
	v_mov_b32_e32 v56, v0
	v_mov_b32_e32 v57, v0
	v_mov_b32_e32 v58, v0
	v_mov_b32_e32 v59, v0
	v_mov_b32_e32 v60, v0
	v_mov_b32_e32 v61, v0
	v_mov_b32_e32 v62, v0
	v_mov_b32_e32 v63, v0
	v_mov_b32_e32 v64, v0
	v_mov_b32_e32 v65, v0
	v_mov_b32_e32 v66, v0
	v_mov_b32_e32 v67, v0
	v_mov_b32_e32 v68, v0
	v_mov_b32_e32 v69, v0
	v_mov_b32_e32 v70, v0
	v_mov_b32_e32 v71, v0
	v_mov_b32_e32 v72, v0
	v_mov_b32_e32 v73, v0
	v_mov_b32_e32 v74, v0
	v_mov_b32_e32 v75, v0
	v_mov_b32_e32 v76, v0
	v_mov_b32_e32 v77, v0
	v_mov_b32_e32 v78, v0
	v_mov_b32_e32 v79, v0
	v_mov_b32_e32 v96, v0
	v_mov_b32_e32 v97, v0
	v_mov_b32_e32 v98, v0
	v_mov_b32_e32 v99, v0
	v_mov_b32_e32 v100, v0
	v_mov_b32_e32 v101, v0
	v_mov_b32_e32 v102, v0
	v_mov_b32_e32 v103, v0
	v_mov_b32_e32 v104, v0
	v_mov_b32_e32 v105, v0
	v_mov_b32_e32 v106, v0
	v_mov_b32_e32 v107, v0
	v_mov_b32_e32 v108, v0
	v_mov_b32_e32 v109, v0
	v_mov_b32_e32 v110, v0
	v_mov_b32_e32 v111, v0
	v_mov_b32_e32 v80, v0
	v_mov_b32_e32 v81, v0
	v_mov_b32_e32 v82, v0
	v_mov_b32_e32 v83, v0
	v_mov_b32_e32 v84, v0
	v_mov_b32_e32 v85, v0
	v_mov_b32_e32 v86, v0
	v_mov_b32_e32 v87, v0
	v_mov_b32_e32 v88, v0
	v_mov_b32_e32 v89, v0
	v_mov_b32_e32 v90, v0
	v_mov_b32_e32 v91, v0
	v_mov_b32_e32 v92, v0
	v_mov_b32_e32 v93, v0
	v_mov_b32_e32 v94, v0
	v_mov_b32_e32 v95, v0
	v_mov_b32_e32 v112, v0
	v_mov_b32_e32 v113, v0
	v_mov_b32_e32 v114, v0
	v_mov_b32_e32 v115, v0
	v_mov_b32_e32 v116, v0
	v_mov_b32_e32 v117, v0
	v_mov_b32_e32 v118, v0
	v_mov_b32_e32 v119, v0
	v_mov_b32_e32 v120, v0
	v_mov_b32_e32 v121, v0
	v_mov_b32_e32 v122, v0
	v_mov_b32_e32 v123, v0
	v_mov_b32_e32 v124, v0
	v_mov_b32_e32 v125, v0
	v_mov_b32_e32 v126, v0
	v_mov_b32_e32 v127, v0
	.p2align 6

.LBB0_907:
	s_ashr_i32 s15, s14, 31
	s_lshl_b64 s[18:19], s[14:15], 20
	s_add_u32 s18, s50, s18
	s_addc_u32 s19, s51, s19
	s_and_b64 s[20:21], s[2:3], exec
	s_cselect_b32 s5, s19, s23
	s_cselect_b32 s15, s18, s22
	s_ashr_i32 s13, s12, 31
	s_lshl_b64 s[20:21], s[12:13], 20
	s_add_u32 s20, s17, s20
	s_addc_u32 s21, s33, s21
	s_and_b64 s[26:27], s[2:3], exec
	s_cselect_b32 s13, s21, s25
	s_cselect_b32 s28, s20, s24
	s_add_u32 s22, s22, 0x80080
	s_addc_u32 s23, s23, 0
	s_add_u32 s29, s24, 0x100
	v_mov_b32_e32 v0, 0
	s_addc_u32 s30, s25, 0
	s_mov_b32 s31, -2
	v_mov_b32_e32 v1, v0
	v_mov_b32_e32 v2, v0
	v_mov_b32_e32 v3, v0
	v_mov_b32_e32 v4, v0
	v_mov_b32_e32 v5, v0
	v_mov_b32_e32 v6, v0
	v_mov_b32_e32 v7, v0
	v_mov_b32_e32 v16, v0
	v_mov_b32_e32 v17, v0
	v_mov_b32_e32 v18, v0
	v_mov_b32_e32 v19, v0
	v_mov_b32_e32 v20, v0
	v_mov_b32_e32 v21, v0
	v_mov_b32_e32 v22, v0
	v_mov_b32_e32 v23, v0
	v_mov_b32_e32 v32, v0
	v_mov_b32_e32 v33, v0
	v_mov_b32_e32 v34, v0
	v_mov_b32_e32 v35, v0
	v_mov_b32_e32 v36, v0
	v_mov_b32_e32 v37, v0
	v_mov_b32_e32 v38, v0
	v_mov_b32_e32 v39, v0
	v_mov_b32_e32 v48, v0
	v_mov_b32_e32 v49, v0
	v_mov_b32_e32 v50, v0
	v_mov_b32_e32 v51, v0
	v_mov_b32_e32 v52, v0
	v_mov_b32_e32 v53, v0
	v_mov_b32_e32 v54, v0
	v_mov_b32_e32 v55, v0
	v_mov_b32_e32 v8, v0
	v_mov_b32_e32 v9, v0
	v_mov_b32_e32 v10, v0
	v_mov_b32_e32 v11, v0
	v_mov_b32_e32 v12, v0
	v_mov_b32_e32 v13, v0
	v_mov_b32_e32 v14, v0
	v_mov_b32_e32 v15, v0
	v_mov_b32_e32 v24, v0
	v_mov_b32_e32 v25, v0
	v_mov_b32_e32 v26, v0
	v_mov_b32_e32 v27, v0
	v_mov_b32_e32 v28, v0
	v_mov_b32_e32 v29, v0
	v_mov_b32_e32 v30, v0
	v_mov_b32_e32 v31, v0
	v_mov_b32_e32 v40, v0
	v_mov_b32_e32 v41, v0
	v_mov_b32_e32 v42, v0
	v_mov_b32_e32 v43, v0
	v_mov_b32_e32 v44, v0
	v_mov_b32_e32 v45, v0
	v_mov_b32_e32 v46, v0
	v_mov_b32_e32 v47, v0
	v_mov_b32_e32 v56, v0
	v_mov_b32_e32 v57, v0
	v_mov_b32_e32 v58, v0
	v_mov_b32_e32 v59, v0
	v_mov_b32_e32 v60, v0
	v_mov_b32_e32 v61, v0
	v_mov_b32_e32 v62, v0
	v_mov_b32_e32 v63, v0
	v_mov_b32_e32 v64, v0
	v_mov_b32_e32 v65, v0
	v_mov_b32_e32 v66, v0
	v_mov_b32_e32 v67, v0
	v_mov_b32_e32 v68, v0
	v_mov_b32_e32 v69, v0
	v_mov_b32_e32 v70, v0
	v_mov_b32_e32 v71, v0
	v_mov_b32_e32 v80, v0
	v_mov_b32_e32 v81, v0
	v_mov_b32_e32 v82, v0
	v_mov_b32_e32 v83, v0
	v_mov_b32_e32 v84, v0
	v_mov_b32_e32 v85, v0
	v_mov_b32_e32 v86, v0
	v_mov_b32_e32 v87, v0
	v_mov_b32_e32 v96, v0
	v_mov_b32_e32 v97, v0
	v_mov_b32_e32 v98, v0
	v_mov_b32_e32 v99, v0
	v_mov_b32_e32 v100, v0
	v_mov_b32_e32 v101, v0
	v_mov_b32_e32 v102, v0
	v_mov_b32_e32 v103, v0
	v_mov_b32_e32 v112, v0
	v_mov_b32_e32 v113, v0
	v_mov_b32_e32 v114, v0
	v_mov_b32_e32 v115, v0
	v_mov_b32_e32 v116, v0
	v_mov_b32_e32 v117, v0
	v_mov_b32_e32 v118, v0
	v_mov_b32_e32 v119, v0
	v_mov_b32_e32 v72, v0
	v_mov_b32_e32 v73, v0
	v_mov_b32_e32 v74, v0
	v_mov_b32_e32 v75, v0
	v_mov_b32_e32 v76, v0
	v_mov_b32_e32 v77, v0
	v_mov_b32_e32 v78, v0
	v_mov_b32_e32 v79, v0
	v_mov_b32_e32 v88, v0
	v_mov_b32_e32 v89, v0
	v_mov_b32_e32 v90, v0
	v_mov_b32_e32 v91, v0
	v_mov_b32_e32 v92, v0
	v_mov_b32_e32 v93, v0
	v_mov_b32_e32 v94, v0
	v_mov_b32_e32 v95, v0
	v_mov_b32_e32 v104, v0
	v_mov_b32_e32 v105, v0
	v_mov_b32_e32 v106, v0
	v_mov_b32_e32 v107, v0
	v_mov_b32_e32 v108, v0
	v_mov_b32_e32 v109, v0
	v_mov_b32_e32 v110, v0
	v_mov_b32_e32 v111, v0
	v_mov_b32_e32 v120, v0
	v_mov_b32_e32 v121, v0
	v_mov_b32_e32 v122, v0
	v_mov_b32_e32 v123, v0
	v_mov_b32_e32 v124, v0
	v_mov_b32_e32 v125, v0
	v_mov_b32_e32 v126, v0
	v_mov_b32_e32 v127, v0
	.p2align 6

.LBB0_1343:
	s_ashr_i32 s11, s10, 31
	s_lshl_b64 s[12:13], s[10:11], 20
	s_add_u32 s12, s50, s12
	s_addc_u32 s13, s51, s13
	s_and_b64 s[14:15], s[2:3], exec
	s_cselect_b32 s11, s13, s19
	s_cselect_b32 s40, s12, s18
	s_ashr_i32 s9, s8, 31
	s_lshl_b64 s[14:15], s[8:9], 20
	s_add_u32 s14, s25, s14
	s_addc_u32 s15, s26, s15
	s_and_b64 s[22:23], s[2:3], exec
	s_cselect_b32 s9, s15, s21
	s_cselect_b32 s41, s14, s20
	s_add_u32 s18, s18, 0x80080
	s_addc_u32 s19, s19, 0
	s_add_u32 s42, s20, 0x100
	v_mov_b32_e32 v0, 0
	s_addc_u32 s43, s21, 0
	s_mov_b32 s44, -2
	v_mov_b32_e32 v1, v0
	v_mov_b32_e32 v2, v0
	v_mov_b32_e32 v3, v0
	v_mov_b32_e32 v4, v0
	v_mov_b32_e32 v5, v0
	v_mov_b32_e32 v6, v0
	v_mov_b32_e32 v7, v0
	v_mov_b32_e32 v8, v0
	v_mov_b32_e32 v9, v0
	v_mov_b32_e32 v10, v0
	v_mov_b32_e32 v11, v0
	v_mov_b32_e32 v12, v0
	v_mov_b32_e32 v13, v0
	v_mov_b32_e32 v14, v0
	v_mov_b32_e32 v15, v0
	v_mov_b32_e32 v32, v0
	v_mov_b32_e32 v33, v0
	v_mov_b32_e32 v34, v0
	v_mov_b32_e32 v35, v0
	v_mov_b32_e32 v36, v0
	v_mov_b32_e32 v37, v0
	v_mov_b32_e32 v38, v0
	v_mov_b32_e32 v39, v0
	v_mov_b32_e32 v40, v0
	v_mov_b32_e32 v41, v0
	v_mov_b32_e32 v42, v0
	v_mov_b32_e32 v43, v0
	v_mov_b32_e32 v44, v0
	v_mov_b32_e32 v45, v0
	v_mov_b32_e32 v46, v0
	v_mov_b32_e32 v47, v0
	v_mov_b32_e32 v16, v0
	v_mov_b32_e32 v17, v0
	v_mov_b32_e32 v18, v0
	v_mov_b32_e32 v19, v0
	v_mov_b32_e32 v20, v0
	v_mov_b32_e32 v21, v0
	v_mov_b32_e32 v22, v0
	v_mov_b32_e32 v23, v0
	v_mov_b32_e32 v24, v0
	v_mov_b32_e32 v25, v0
	v_mov_b32_e32 v26, v0
	v_mov_b32_e32 v27, v0
	v_mov_b32_e32 v28, v0
	v_mov_b32_e32 v29, v0
	v_mov_b32_e32 v30, v0
	v_mov_b32_e32 v31, v0
	v_mov_b32_e32 v48, v0
	v_mov_b32_e32 v49, v0
	v_mov_b32_e32 v50, v0
	v_mov_b32_e32 v51, v0
	v_mov_b32_e32 v52, v0
	v_mov_b32_e32 v53, v0
	v_mov_b32_e32 v54, v0
	v_mov_b32_e32 v55, v0
	v_mov_b32_e32 v56, v0
	v_mov_b32_e32 v57, v0
	v_mov_b32_e32 v58, v0
	v_mov_b32_e32 v59, v0
	v_mov_b32_e32 v60, v0
	v_mov_b32_e32 v61, v0
	v_mov_b32_e32 v62, v0
	v_mov_b32_e32 v63, v0
	v_mov_b32_e32 v64, v0
	v_mov_b32_e32 v65, v0
	v_mov_b32_e32 v66, v0
	v_mov_b32_e32 v67, v0
	v_mov_b32_e32 v68, v0
	v_mov_b32_e32 v69, v0
	v_mov_b32_e32 v70, v0
	v_mov_b32_e32 v71, v0
	v_mov_b32_e32 v72, v0
	v_mov_b32_e32 v73, v0
	v_mov_b32_e32 v74, v0
	v_mov_b32_e32 v75, v0
	v_mov_b32_e32 v76, v0
	v_mov_b32_e32 v77, v0
	v_mov_b32_e32 v78, v0
	v_mov_b32_e32 v79, v0
	v_mov_b32_e32 v96, v0
	v_mov_b32_e32 v97, v0
	v_mov_b32_e32 v98, v0
	v_mov_b32_e32 v99, v0
	v_mov_b32_e32 v100, v0
	v_mov_b32_e32 v101, v0
	v_mov_b32_e32 v102, v0
	v_mov_b32_e32 v103, v0
	v_mov_b32_e32 v104, v0
	v_mov_b32_e32 v105, v0
	v_mov_b32_e32 v106, v0
	v_mov_b32_e32 v107, v0
	v_mov_b32_e32 v108, v0
	v_mov_b32_e32 v109, v0
	v_mov_b32_e32 v110, v0
	v_mov_b32_e32 v111, v0
	v_mov_b32_e32 v80, v0
	v_mov_b32_e32 v81, v0
	v_mov_b32_e32 v82, v0
	v_mov_b32_e32 v83, v0
	v_mov_b32_e32 v84, v0
	v_mov_b32_e32 v85, v0
	v_mov_b32_e32 v86, v0
	v_mov_b32_e32 v87, v0
	v_mov_b32_e32 v88, v0
	v_mov_b32_e32 v89, v0
	v_mov_b32_e32 v90, v0
	v_mov_b32_e32 v91, v0
	v_mov_b32_e32 v92, v0
	v_mov_b32_e32 v93, v0
	v_mov_b32_e32 v94, v0
	v_mov_b32_e32 v95, v0
	v_mov_b32_e32 v112, v0
	v_mov_b32_e32 v113, v0
	v_mov_b32_e32 v114, v0
	v_mov_b32_e32 v115, v0
	v_mov_b32_e32 v116, v0
	v_mov_b32_e32 v117, v0
	v_mov_b32_e32 v118, v0
	v_mov_b32_e32 v119, v0
	v_mov_b32_e32 v120, v0
	v_mov_b32_e32 v121, v0
	v_mov_b32_e32 v122, v0
	v_mov_b32_e32 v123, v0
	v_mov_b32_e32 v124, v0
	v_mov_b32_e32 v125, v0
	v_mov_b32_e32 v126, v0
	v_mov_b32_e32 v127, v0
	.p2align 6

.LBB0_1479:
	s_ashr_i32 s29, s28, 31
	s_lshl_b64 s[30:31], s[28:29], 20
	s_add_u32 s30, s50, s30
	s_addc_u32 s31, s51, s31
	s_and_b64 s[34:35], s[2:3], exec
	s_cselect_b32 s0, s31, s39
	s_cselect_b32 s5, s30, s38
	s_ashr_i32 s27, s26, 31
	s_lshl_b64 s[34:35], s[26:27], 20
	s_add_u32 s34, s25, s34
	s_addc_u32 s35, s46, s35
	s_and_b64 s[42:43], s[2:3], exec
	s_cselect_b32 s27, s35, s41
	s_cselect_b32 s29, s34, s40
	s_add_u32 s38, s38, 0x80080
	s_addc_u32 s39, s39, 0
	s_add_u32 s33, s40, 0x100
	v_mov_b32_e32 v0, 0
	s_addc_u32 s44, s41, 0
	s_mov_b32 s45, -2
	v_mov_b32_e32 v1, v0
	v_mov_b32_e32 v2, v0
	v_mov_b32_e32 v3, v0
	v_mov_b32_e32 v4, v0
	v_mov_b32_e32 v5, v0
	v_mov_b32_e32 v6, v0
	v_mov_b32_e32 v7, v0
	v_mov_b32_e32 v16, v0
	v_mov_b32_e32 v17, v0
	v_mov_b32_e32 v18, v0
	v_mov_b32_e32 v19, v0
	v_mov_b32_e32 v20, v0
	v_mov_b32_e32 v21, v0
	v_mov_b32_e32 v22, v0
	v_mov_b32_e32 v23, v0
	v_mov_b32_e32 v32, v0
	v_mov_b32_e32 v33, v0
	v_mov_b32_e32 v34, v0
	v_mov_b32_e32 v35, v0
	v_mov_b32_e32 v36, v0
	v_mov_b32_e32 v37, v0
	v_mov_b32_e32 v38, v0
	v_mov_b32_e32 v39, v0
	v_mov_b32_e32 v48, v0
	v_mov_b32_e32 v49, v0
	v_mov_b32_e32 v50, v0
	v_mov_b32_e32 v51, v0
	v_mov_b32_e32 v52, v0
	v_mov_b32_e32 v53, v0
	v_mov_b32_e32 v54, v0
	v_mov_b32_e32 v55, v0
	v_mov_b32_e32 v8, v0
	v_mov_b32_e32 v9, v0
	v_mov_b32_e32 v10, v0
	v_mov_b32_e32 v11, v0
	v_mov_b32_e32 v12, v0
	v_mov_b32_e32 v13, v0
	v_mov_b32_e32 v14, v0
	v_mov_b32_e32 v15, v0
	v_mov_b32_e32 v24, v0
	v_mov_b32_e32 v25, v0
	v_mov_b32_e32 v26, v0
	v_mov_b32_e32 v27, v0
	v_mov_b32_e32 v28, v0
	v_mov_b32_e32 v29, v0
	v_mov_b32_e32 v30, v0
	v_mov_b32_e32 v31, v0
	v_mov_b32_e32 v40, v0
	v_mov_b32_e32 v41, v0
	v_mov_b32_e32 v42, v0
	v_mov_b32_e32 v43, v0
	v_mov_b32_e32 v44, v0
	v_mov_b32_e32 v45, v0
	v_mov_b32_e32 v46, v0
	v_mov_b32_e32 v47, v0
	v_mov_b32_e32 v56, v0
	v_mov_b32_e32 v57, v0
	v_mov_b32_e32 v58, v0
	v_mov_b32_e32 v59, v0
	v_mov_b32_e32 v60, v0
	v_mov_b32_e32 v61, v0
	v_mov_b32_e32 v62, v0
	v_mov_b32_e32 v63, v0
	v_mov_b32_e32 v64, v0
	v_mov_b32_e32 v65, v0
	v_mov_b32_e32 v66, v0
	v_mov_b32_e32 v67, v0
	v_mov_b32_e32 v68, v0
	v_mov_b32_e32 v69, v0
	v_mov_b32_e32 v70, v0
	v_mov_b32_e32 v71, v0
	v_mov_b32_e32 v80, v0
	v_mov_b32_e32 v81, v0
	v_mov_b32_e32 v82, v0
	v_mov_b32_e32 v83, v0
	v_mov_b32_e32 v84, v0
	v_mov_b32_e32 v85, v0
	v_mov_b32_e32 v86, v0
	v_mov_b32_e32 v87, v0
	v_mov_b32_e32 v96, v0
	v_mov_b32_e32 v97, v0
	v_mov_b32_e32 v98, v0
	v_mov_b32_e32 v99, v0
	v_mov_b32_e32 v100, v0
	v_mov_b32_e32 v101, v0
	v_mov_b32_e32 v102, v0
	v_mov_b32_e32 v103, v0
	v_mov_b32_e32 v112, v0
	v_mov_b32_e32 v113, v0
	v_mov_b32_e32 v114, v0
	v_mov_b32_e32 v115, v0
	v_mov_b32_e32 v116, v0
	v_mov_b32_e32 v117, v0
	v_mov_b32_e32 v118, v0
	v_mov_b32_e32 v119, v0
	v_mov_b32_e32 v72, v0
	v_mov_b32_e32 v73, v0
	v_mov_b32_e32 v74, v0
	v_mov_b32_e32 v75, v0
	v_mov_b32_e32 v76, v0
	v_mov_b32_e32 v77, v0
	v_mov_b32_e32 v78, v0
	v_mov_b32_e32 v79, v0
	v_mov_b32_e32 v88, v0
	v_mov_b32_e32 v89, v0
	v_mov_b32_e32 v90, v0
	v_mov_b32_e32 v91, v0
	v_mov_b32_e32 v92, v0
	v_mov_b32_e32 v93, v0
	v_mov_b32_e32 v94, v0
	v_mov_b32_e32 v95, v0
	v_mov_b32_e32 v104, v0
	v_mov_b32_e32 v105, v0
	v_mov_b32_e32 v106, v0
	v_mov_b32_e32 v107, v0
	v_mov_b32_e32 v108, v0
	v_mov_b32_e32 v109, v0
	v_mov_b32_e32 v110, v0
	v_mov_b32_e32 v111, v0
	v_mov_b32_e32 v120, v0
	v_mov_b32_e32 v121, v0
	v_mov_b32_e32 v122, v0
	v_mov_b32_e32 v123, v0
	v_mov_b32_e32 v124, v0
	v_mov_b32_e32 v125, v0
	v_mov_b32_e32 v126, v0
	v_mov_b32_e32 v127, v0
	.p2align 6

.LBB0_1604:
	v_sub_f32_e32 v0, v18, v186
	v_exp_f32_e32 v0, v0
	v_sub_f32_e32 v18, v19, v186
	v_exp_f32_e32 v18, v18
	v_sub_f32_e32 v19, v20, v186
	v_exp_f32_e32 v19, v19
	v_sub_f32_e32 v20, v21, v186
	v_exp_f32_e32 v20, v20
	v_sub_f32_e32 v22, v22, v186
	v_add_f32_e32 v21, 0, v0
	v_exp_f32_e32 v22, v22
	v_sub_f32_e32 v23, v23, v186
	v_add_f32_e32 v21, v18, v21
	v_exp_f32_e32 v23, v23
	v_sub_f32_e32 v24, v24, v186
	v_add_f32_e32 v21, v19, v21
	v_exp_f32_e32 v24, v24
	v_sub_f32_e32 v25, v25, v186
	v_add_f32_e32 v21, v20, v21
	v_exp_f32_e32 v25, v25
	v_sub_f32_e32 v26, v26, v186
	v_add_f32_e32 v21, v22, v21
	v_exp_f32_e32 v26, v26
	v_sub_f32_e32 v27, v27, v186
	v_add_f32_e32 v21, v23, v21
	v_exp_f32_e32 v27, v27
	v_sub_f32_e32 v28, v28, v186
	v_add_f32_e32 v21, v24, v21
	v_exp_f32_e32 v28, v28
	v_sub_f32_e32 v29, v29, v186
	v_add_f32_e32 v21, v25, v21
	v_exp_f32_e32 v29, v29
	v_sub_f32_e32 v30, v30, v186
	v_add_f32_e32 v21, v26, v21
	v_exp_f32_e32 v30, v30
	v_sub_f32_e32 v31, v31, v186
	v_add_f32_e32 v21, v27, v21
	v_exp_f32_e32 v31, v31
	v_sub_f32_e32 v32, v32, v186
	v_add_f32_e32 v21, v28, v21
	v_exp_f32_e32 v32, v32
	v_sub_f32_e32 v33, v33, v186
	v_add_f32_e32 v21, v29, v21
	v_exp_f32_e32 v33, v33
	v_add_f32_e32 v21, v30, v21
	v_add_f32_e32 v21, v31, v21
	v_cvt_pk_bf16_f32 v182, v0, v18
	v_add_u32_e32 v0, s3, v242
	v_add_f32_e32 v21, v32, v21
	v_cvt_pk_bf16_f32 v183, v19, v20
	v_lshlrev_b64 v[18:19], 9, v[0:1]
	v_add_u32_e32 v0, s3, v243
	v_add_f32_e32 v203, v33, v21
	v_lshl_add_u64 v[204:205], v[40:41], 0, v[18:19]
	v_lshlrev_b64 v[18:19], 9, v[0:1]
	s_lshl_b32 s41, s2, 2
	v_cvt_pk_bf16_f32 v178, v26, v27
	v_cvt_pk_bf16_f32 v179, v28, v29
	v_cvt_pk_bf16_f32 v180, v30, v31
	v_cvt_pk_bf16_f32 v181, v32, v33
	v_cvt_pk_bf16_f32 v184, v22, v23
	v_cvt_pk_bf16_f32 v185, v24, v25
	v_fmac_f32_e32 v203, 0, v42
	v_lshl_add_u64 v[206:207], v[38:39], 0, v[18:19]
	v_lshl_add_u64 v[208:209], v[36:37], 0, s[16:17]
	v_lshl_add_u64 v[210:211], v[34:35], 0, s[16:17]
	v_mov_b64_e32 v[32:33], v[16:17]
	v_mov_b64_e32 v[48:49], v[16:17]
	v_mov_b64_e32 v[64:65], v[16:17]
	v_mov_b64_e32 v[80:81], v[16:17]
	v_mov_b64_e32 v[96:97], v[16:17]
	v_mov_b64_e32 v[112:113], v[16:17]
	v_mov_b64_e32 v[128:129], v[16:17]
	s_add_i32 s42, s41, 4
	s_add_i32 s43, s33, 0x60
	s_mov_b32 s0, 1
	s_mov_b32 s44, 0
	s_mov_b32 s45, 3
	v_mov_b64_e32 v[30:31], v[14:15]
	v_mov_b64_e32 v[28:29], v[12:13]
	v_mov_b64_e32 v[26:27], v[10:11]
	v_mov_b64_e32 v[24:25], v[8:9]
	v_mov_b64_e32 v[22:23], v[6:7]
	v_mov_b64_e32 v[20:21], v[4:5]
	v_mov_b64_e32 v[18:19], v[2:3]
	v_mov_b64_e32 v[46:47], v[14:15]
	v_mov_b64_e32 v[44:45], v[12:13]
	v_mov_b64_e32 v[42:43], v[10:11]
	v_mov_b64_e32 v[40:41], v[8:9]
	v_mov_b64_e32 v[38:39], v[6:7]
	v_mov_b64_e32 v[36:37], v[4:5]
	v_mov_b64_e32 v[34:35], v[2:3]
	v_mov_b64_e32 v[62:63], v[14:15]
	v_mov_b64_e32 v[60:61], v[12:13]
	v_mov_b64_e32 v[58:59], v[10:11]
	v_mov_b64_e32 v[56:57], v[8:9]
	v_mov_b64_e32 v[54:55], v[6:7]
	v_mov_b64_e32 v[52:53], v[4:5]
	v_mov_b64_e32 v[50:51], v[2:3]
	v_mov_b64_e32 v[78:79], v[14:15]
	v_mov_b64_e32 v[76:77], v[12:13]
	v_mov_b64_e32 v[74:75], v[10:11]
	v_mov_b64_e32 v[72:73], v[8:9]
	v_mov_b64_e32 v[70:71], v[6:7]
	v_mov_b64_e32 v[68:69], v[4:5]
	v_mov_b64_e32 v[66:67], v[2:3]
	v_mov_b64_e32 v[94:95], v[14:15]
	v_mov_b64_e32 v[92:93], v[12:13]
	v_mov_b64_e32 v[90:91], v[10:11]
	v_mov_b64_e32 v[88:89], v[8:9]
	v_mov_b64_e32 v[86:87], v[6:7]
	v_mov_b64_e32 v[84:85], v[4:5]
	v_mov_b64_e32 v[82:83], v[2:3]
	v_mov_b64_e32 v[110:111], v[14:15]
	v_mov_b64_e32 v[108:109], v[12:13]
	v_mov_b64_e32 v[106:107], v[10:11]
	v_mov_b64_e32 v[104:105], v[8:9]
	v_mov_b64_e32 v[102:103], v[6:7]
	v_mov_b64_e32 v[100:101], v[4:5]
	v_mov_b64_e32 v[98:99], v[2:3]
	v_mov_b64_e32 v[126:127], v[14:15]
	v_mov_b64_e32 v[124:125], v[12:13]
	v_mov_b64_e32 v[122:123], v[10:11]
	v_mov_b64_e32 v[120:121], v[8:9]
	v_mov_b64_e32 v[118:119], v[6:7]
	v_mov_b64_e32 v[116:117], v[4:5]
	v_mov_b64_e32 v[114:115], v[2:3]
	s_mov_b32 s47, 0
	.p2align 6
